# m1 step 1: wave 0's 64-lane inclusive prefix sum of g via DPP row_shr / row_bcast adds instead of six ds_bpermute round trips (paired re-test on the current best)
# baseline (speedup 1.0000x reference)
.LBB0_554:
	v_lshl_add_u32 v2, v36, 2, 0
	v_add_u32_e32 v3, 0x19600, v2
	v_mov_b32_e32 v0, v29
	s_nop 1
	v_add_f32_dpp v0, v0, v0 row_shr:1 row_mask:0xf bank_mask:0xf
	s_nop 1
	v_add_f32_dpp v0, v0, v0 row_shr:2 row_mask:0xf bank_mask:0xf
	s_nop 1
	v_add_f32_dpp v0, v0, v0 row_shr:4 row_mask:0xf bank_mask:0xf
	s_nop 1
	v_add_f32_dpp v0, v0, v0 row_shr:8 row_mask:0xf bank_mask:0xf
	s_nop 1
	v_add_f32_dpp v0, v0, v0 row_bcast:15 row_mask:0xa bank_mask:0xf
	s_nop 1
	v_add_f32_dpp v0, v0, v0 row_bcast:31 row_mask:0xc bank_mask:0xf
	s_nop 1
	v_mul_f32_e32 v1, 0x3fb8aa3b, v0
	v_exp_f32_e32 v1, v1
	ds_write_b32 v3, v0
	v_add_u32_e32 v0, 0x19700, v2
	ds_write_b32 v0, v28
	v_add_u32_e32 v0, 0x19800, v2
	ds_write_b32 v0, v1
	v_mul_f32_e32 v0, v28, v1
	v_add_u32_e32 v1, 0x19900, v2
	ds_write_b32 v1, v0
